# v12 + nt (streaming) cache policy on rout phase global loads and Y stores
# speedup vs baseline: 1.0033x; 1.0033x over previous
; #define LAS __attribute__((address_space(3)))
; #define RO_WRITE(rv, rs, buf) do { _Pragma("unroll") for (int i = 0; i < 2; ++i) { const int q = tid + 512 * i; *(LAS v4u*)(lds + (buf) + (q >> 4) * VROW + (q & 15) * 16) = rv[i]; } \
;             if (cross) { _Pragma("unroll") for (int i = 0; i < 4; ++i) { const int q = tid + 512 * i; *(LAS v4u*)(lds + (buf) + VTB + (q >> 5) * SROW + (q & 31) * 16) = rs[i]; } } } while (0)
; __device__ __forceinline__ void ret_out_phase(LAS unsigned char* lds, const bf16* PROJ, const bf16* KVT, const bf16* ST, bf16* Y, float* RN, int G, int bid) {
;     ...
;     for (int u = bid; u < 512; u += G) {
;         asm volatile("" : "+v"(tid_));
;         const int tid = tid_, lane = tid & 63, w = __builtin_amdgcn_readfirstlane(tid >> 6), g = lane >> 4, li = lane & 15;
;         const int h = u >> 6, c = u & 63, t0 = c * 128, n0 = 16 * w;
;         const bool cross = (c > 0);
;         bf16x8 qf[8];
; #pragma unroll
;         for (int ks = 0; ks < 8; ++ks) qf[ks] = *(const bf16x8*)(PROJ + (size_t)(t0 + n0 + li) * 6144 + h * 256 + 32 * ks + 8 * g);
;         {
;             v4u rk[8];
; #pragma unroll
;             for (int i = 0; i < 8; ++i) { const int q = tid + 512 * i; rk[i] = *(const v4u*)(KVT + (size_t)(h * 256 + (q >> 4)) * KVT_LD + t0 + (q & 15) * 8); }
; #pragma unroll
;             for (int i = 0; i < 8; ++i) { const int q = tid + 512 * i; *(LAS v4u*)(lds + KS + (q >> 4) * KROW + (q & 15) * 16) = rk[i]; }
;         }
;         v4u rvA[2], rsA[4];
;     ...
;         RO_LOAD(rvA, rsA, 0); RO_WRITE(rvA, rsA, BUF0);
.LBB0_105:
	s_and_b32 s3, s20, 63
	v_readfirstlane_b32 s0, v111
	s_ashr_i32 s1, s0, 6
	s_lshl_b32 s0, s3, 7
	s_lshl_b32 s10, s1, 4
	v_and_b32_e32 v98, 15, v111
	s_add_i32 s0, s10, s0
	v_or_b32_e32 v2, s0, v98
	s_waitcnt lgkmcnt(0)
	v_mov_b64_e32 v[8:9], s[40:41]
	s_movk_i32 s0, 0x3000
	s_ashr_i32 s2, s20, 6
	v_mad_i64_i32 v[8:9], s[4:5], v2, s0, v[8:9]
	s_lshl_b32 s4, s2, 8
	s_ashr_i32 s5, s4, 31
	s_lshl_b32 s0, s3, 8
	v_readlane_b32 s12, v253, 22
	v_readlane_b32 s13, v253, 23
	s_add_u32 s12, s12, s0
	v_lshlrev_b32_e32 v101, 4, v111
	s_addc_u32 s13, s13, 0
	v_and_b32_e32 v94, 0xf0, v101
	v_mov_b32_e32 v95, v1
	v_ashrrev_i32_e32 v99, 4, v111
	v_add_u32_e32 v82, 0x200, v111
	v_lshl_add_u64 v[108:109], s[12:13], 0, v[94:95]
	v_add_u32_e32 v3, s4, v99
	s_movk_i32 s22, 0x4080
	v_ashrrev_i32_e32 v100, 4, v82
	v_mad_i64_i32 v[56:57], s[12:13], v3, s22, v[108:109]
	v_add_u32_e32 v3, s4, v100
	v_lshl_add_u64 v[8:9], s[4:5], 1, v[8:9]
	v_and_b32_e32 v0, 48, v111
	v_mad_i64_i32 v[60:61], s[12:13], v3, s22, v[108:109]
	v_add_u32_e32 v3, 0x400, v111
	v_lshl_add_u64 v[36:37], v[8:9], 0, v[0:1]
	v_ashrrev_i32_e32 v65, 4, v3
	v_add_u32_e32 v88, 0x600, v111
	global_load_dwordx4 v[8:11], v[36:37], off nt
	global_load_dwordx4 v[12:15], v[36:37], off offset:64 nt
	global_load_dwordx4 v[16:19], v[36:37], off offset:128 nt
	global_load_dwordx4 v[20:23], v[36:37], off offset:192 nt
	global_load_dwordx4 v[24:27], v[36:37], off offset:256 nt
	global_load_dwordx4 v[28:31], v[36:37], off offset:320 nt
	global_load_dwordx4 v[32:35], v[36:37], off offset:384 nt
	s_nop 0
	global_load_dwordx4 v[36:39], v[36:37], off offset:448 nt
	v_add_u32_e32 v66, s4, v65
	global_load_dwordx4 v[56:59], v[56:57], off nt
	v_ashrrev_i32_e32 v83, 4, v88
	s_waitcnt vmcnt(0)
	v_add_u32_e32 v74, 0x800, v111
	v_mad_i64_i32 v[66:67], s[12:13], v66, s22, v[108:109]
	v_add_u32_e32 v70, s4, v83
	v_ashrrev_i32_e32 v89, 4, v74
	v_add_u32_e32 v78, 0xa00, v111
	global_load_dwordx4 v[60:63], v[60:61], off nt
	v_mad_i64_i32 v[70:71], s[12:13], v70, s22, v[108:109]
	global_load_dwordx4 v[66:69], v[66:67], off nt
	v_add_u32_e32 v74, s4, v89
	v_ashrrev_i32_e32 v95, 4, v78
	v_add_u32_e32 v84, 0xc00, v111
	global_load_dwordx4 v[70:73], v[70:71], off nt
	v_mad_i64_i32 v[74:75], s[12:13], v74, s22, v[108:109]
	v_add_u32_e32 v78, s4, v95
	v_ashrrev_i32_e32 v96, 4, v84
	global_load_dwordx4 v[74:77], v[74:75], off nt
	v_mad_i64_i32 v[78:79], s[12:13], v78, s22, v[108:109]
	v_add_u32_e32 v84, s4, v96
	v_add_u32_e32 v90, 0xe00, v111
	global_load_dwordx4 v[78:81], v[78:79], off nt
	v_mad_i64_i32 v[84:85], s[12:13], v84, s22, v[108:109]
	v_ashrrev_i32_e32 v97, 4, v90
	global_load_dwordx4 v[84:87], v[84:85], off nt
	v_add_u32_e32 v90, s4, v97
	v_mad_i64_i32 v[90:91], s[4:5], v90, s22, v[108:109]
	global_load_dwordx4 v[90:93], v[90:91], off nt
	s_movk_i32 s0, 0x110
	v_add_u32_e32 v94, 0, v94
	v_mul_lo_u32 v102, v99, s0
	v_add_u32_e32 v156, v94, v102
	v_lshlrev_b32_e32 v64, 3, v111
	s_movk_i32 s23, 0x110
	v_ashrrev_i32_e32 v104, 5, v111
	v_ashrrev_i32_e32 v105, 5, v82
	v_ashrrev_i32_e32 v106, 5, v3
	v_ashrrev_i32_e32 v107, 5, v88
	s_waitcnt vmcnt(7)
	ds_write_b128 v156, v[56:59] offset:51200
	v_mul_lo_u32 v56, v100, s0
	v_add_u32_e32 v157, v94, v56
	v_mad_u64_u32 v[56:57], s[4:5], v65, s0, v[94:95]
	s_waitcnt vmcnt(6)
	ds_write_b128 v157, v[60:63] offset:51200
	s_waitcnt vmcnt(5)
	ds_write_b128 v56, v[66:69] offset:51200
	v_mad_u64_u32 v[56:57], s[4:5], v83, s0, v[94:95]
	s_waitcnt vmcnt(4)
	ds_write_b128 v56, v[70:73] offset:51200
	v_mad_u64_u32 v[56:57], s[4:5], v89, s0, v[94:95]
	s_waitcnt vmcnt(3)
	ds_write_b128 v56, v[74:77] offset:51200
	v_mad_u64_u32 v[56:57], s[4:5], v95, s0, v[94:95]
	s_waitcnt vmcnt(2)
	ds_write_b128 v56, v[78:81] offset:51200
	v_mad_u64_u32 v[56:57], s[4:5], v96, s0, v[94:95]
	v_and_b32_e32 v96, 0xf8, v64
	s_waitcnt vmcnt(1)
	ds_write_b128 v56, v[84:87] offset:51200
	v_mad_u64_u32 v[56:57], s[4:5], v97, s0, v[94:95]
	s_lshl_b32 s0, s2, 9
	s_add_i32 s11, s0, 0x800
	s_waitcnt vmcnt(0)
	ds_write_b128 v56, v[90:93] offset:51200
	v_add_u32_e32 v56, s11, v99
	v_add_u32_e32 v60, s11, v100
	v_mad_i64_i32 v[56:57], s[4:5], v56, s22, v[108:109]
	v_mad_i64_i32 v[60:61], s[4:5], v60, s22, v[108:109]
	global_load_dwordx4 v[56:59], v[56:57], off nt
	s_cmp_lg_u32 s3, 0
	global_load_dwordx4 v[60:63], v[60:61], off nt
	s_cselect_b64 s[4:5], -1, 0
	s_cmp_eq_u32 s3, 0
	v_lshlrev_b32_e32 v80, 1, v96
	s_cbranch_scc1 .LBB0_107
	s_lshl_b32 s3, s20, 9
	v_ashrrev_i32_e32 v40, 5, v111
	v_ashrrev_i32_e32 v42, 5, v82
	v_ashrrev_i32_e32 v50, 5, v3
	v_ashrrev_i32_e32 v52, 5, v88
	v_readlane_b32 s12, v253, 24
	v_add_u32_e32 v40, s3, v40
	v_add_u32_e32 v42, s3, v42
	v_add_u32_e32 v50, s3, v50
	v_add_u32_e32 v52, s3, v52
	v_mov_b32_e32 v81, v1
	v_readlane_b32 s13, v253, 25
	v_ashrrev_i32_e32 v41, 31, v40
	v_ashrrev_i32_e32 v43, 31, v42
	v_ashrrev_i32_e32 v51, 31, v50
	v_ashrrev_i32_e32 v53, 31, v52
	v_lshl_add_u64 v[48:49], s[12:13], 0, v[80:81]
	v_lshlrev_b64 v[40:41], 9, v[40:41]
	v_lshlrev_b64 v[42:43], 9, v[42:43]
	v_lshlrev_b64 v[50:51], 9, v[50:51]
	v_lshlrev_b64 v[52:53], 9, v[52:53]
	v_lshl_add_u64 v[40:41], v[48:49], 0, v[40:41]
	v_lshl_add_u64 v[44:45], v[48:49], 0, v[42:43]
	v_lshl_add_u64 v[50:51], v[48:49], 0, v[50:51]
	v_lshl_add_u64 v[52:53], v[48:49], 0, v[52:53]
	global_load_dwordx4 v[40:43], v[40:41], off nt
	s_nop 0
	global_load_dwordx4 v[44:47], v[44:45], off nt
	s_nop 0
	global_load_dwordx4 v[48:51], v[50:51], off nt
	s_nop 0
	global_load_dwordx4 v[52:55], v[52:53], off nt

; #define LBAR() do { asm volatile("s_waitcnt lgkmcnt(0)" ::: "memory"); __builtin_amdgcn_s_barrier(); asm volatile("" ::: "memory"); } while (0)
; __device__ __forceinline__ bf16x8 pack8(f32x4 a, f32x4 b) { v4u w; w.x = pk2(a[0], a[1]); w.y = pk2(a[2], a[3]); w.z = pk2(b[0], b[1]); w.w = pk2(b[2], b[3]); return __builtin_bit_cast(bf16x8, w); }
; __device__ __forceinline__ void ret_out_phase(LAS unsigned char* lds, const bf16* PROJ, const bf16* KVT, const bf16* ST, bf16* Y, float* RN, int G, int bid) {
;     ...
;             for (int i = 0; i < 4; ++i) pf[i] = pack8(sacc[2 * i], sacc[2 * i + 1]);
;         }
;         LBAR();
;         RO_LOAD(rvA, rsA, 1);
.LBB0_125:
	s_add_i32 s3, s0, 0x840
	v_cvt_pk_bf16_f32 v56, v59, v60
	v_cvt_pk_bf16_f32 v57, v61, v62
	v_cvt_pk_bf16_f32 v58, v58, v64
	v_cvt_pk_bf16_f32 v59, v65, v66
	v_cvt_pk_bf16_f32 v60, v68, v69
	v_cvt_pk_bf16_f32 v61, v70, v71
	v_cvt_pk_bf16_f32 v62, v67, v72
	v_cvt_pk_bf16_f32 v63, v73, v74
	v_add_u32_e32 v72, s3, v99
	s_movk_i32 s11, 0x4080
	v_add_u32_e32 v74, s3, v100
	v_cvt_pk_bf16_f32 v64, v76, v77
	v_cvt_pk_bf16_f32 v65, v78, v79
	v_cvt_pk_bf16_f32 v66, v75, v81
	v_cvt_pk_bf16_f32 v67, v83, v84
	v_cvt_pk_bf16_f32 v68, v86, v87
	v_cvt_pk_bf16_f32 v69, v89, v90
	v_cvt_pk_bf16_f32 v70, v85, v91
	v_cvt_pk_bf16_f32 v71, v92, v93
	s_waitcnt lgkmcnt(0)
	s_barrier
	v_mad_i64_i32 v[72:73], s[12:13], v72, s11, v[108:109]
	v_mad_i64_i32 v[74:75], s[12:13], v74, s11, v[108:109]
	global_load_dwordx4 v[76:79], v[72:73], off nt
	s_nop 0
	global_load_dwordx4 v[72:75], v[74:75], off nt
	s_and_b64 vcc, exec, s[4:5]
	s_cbranch_vccz .LBB0_174
	s_lshl_b32 s3, s20, 9
	v_readlane_b32 s4, v253, 24
	s_or_b32 s3, s3, 64
	v_mov_b32_e32 v81, v1
	v_readlane_b32 s5, v253, 25
	v_ashrrev_i32_e32 v118, 5, v111
	v_ashrrev_i32_e32 v119, 5, v82
	v_ashrrev_i32_e32 v120, 5, v3
	v_ashrrev_i32_e32 v121, 5, v88
	v_lshl_add_u64 v[90:91], s[4:5], 0, v[80:81]
	v_add_u32_e32 v80, s3, v118
	v_add_u32_e32 v82, s3, v119
	v_add_u32_e32 v92, s3, v120
	v_add_u32_e32 v88, s3, v121
	v_ashrrev_i32_e32 v81, 31, v80
	v_ashrrev_i32_e32 v83, 31, v82
	v_ashrrev_i32_e32 v93, 31, v92
	v_ashrrev_i32_e32 v89, 31, v88
	v_lshlrev_b64 v[80:81], 9, v[80:81]
	v_lshlrev_b64 v[82:83], 9, v[82:83]
	v_lshlrev_b64 v[92:93], 9, v[92:93]
	v_lshlrev_b64 v[88:89], 9, v[88:89]
	v_lshl_add_u64 v[80:81], v[90:91], 0, v[80:81]
	v_lshl_add_u64 v[84:85], v[90:91], 0, v[82:83]
	v_lshl_add_u64 v[92:93], v[90:91], 0, v[92:93]
	v_lshl_add_u64 v[94:95], v[90:91], 0, v[88:89]
	global_load_dwordx4 v[80:83], v[80:81], off nt
	s_nop 0
	global_load_dwordx4 v[84:87], v[84:85], off nt
	s_nop 0
	global_load_dwordx4 v[88:91], v[92:93], off nt
	s_nop 0
	global_load_dwordx4 v[92:95], v[94:95], off nt
	v_mov_b32_e32 v97, v1
	s_cbranch_execnz .LBB0_128

.LBB0_136:
	v_lshl_add_u64 v[140:141], v[118:119], 0, s[0:1]
	s_mov_b32 s4, 0xf501000
	v_add_co_u32_e32 v142, vcc, s4, v140
	s_nop 4
	v_pk_mul_f32 v[128:129], v[114:115], v[98:99]
	v_addc_co_u32_e32 v143, vcc, 0, v141, vcc
	s_waitcnt lgkmcnt(0)
	v_add_co_u32_e32 v80, vcc, 0xf519000, v140
	v_pk_mul_f32 v[130:131], v[112:113], v[96:97]
	s_nop 0
	v_addc_co_u32_e32 v81, vcc, 0, v141, vcc
	v_cvt_pk_bf16_f32 v88, v130, v131
	v_cvt_pk_bf16_f32 v89, v128, v129
	global_load_dwordx4 v[84:87], v[142:143], off nt
	s_nop 0
	global_load_dwordx4 v[80:83], v[80:81], off nt
	ds_write_b64 v175, v[88:89] offset:32
	v_add_u32_e32 v88, 0x2000, v174
	ds_read2_b64 v[96:99], v88 offset0:64 offset1:68
	ds_read2_b64 v[92:95], v88 offset0:72 offset1:76
	ds_read2_b64 v[100:103], v88 offset0:80 offset1:84
	ds_read2_b64 v[88:91], v88 offset0:88 offset1:92
	s_and_b64 vcc, exec, s[38:39]
	s_cbranch_vccnz .LBB0_166
	ds_read_b128 v[104:107], v136 offset:25856
	ds_read_b128 v[132:135], v136 offset:25920
	ds_read_b128 v[144:147], v136 offset:25984
	ds_read_b128 v[148:151], v136 offset:26048
	s_waitcnt lgkmcnt(7)
	v_mfma_f32_16x16x32_bf16 v[152:155], v[96:99], v[56:59], 0
	ds_read_b128 v[178:181], v136 offset:26112
	ds_read_b128 v[184:187], v136 offset:26176
	ds_read_b128 v[188:191], v136 offset:26240
	ds_read_b128 v[192:195], v136 offset:26304
	s_waitcnt lgkmcnt(10)
	v_mfma_f32_16x16x32_bf16 v[152:155], v[92:95], v[60:63], v[152:155]
	s_waitcnt lgkmcnt(9)
	v_mfma_f32_16x16x32_bf16 v[152:155], v[100:103], v[64:67], v[152:155]
	s_waitcnt lgkmcnt(8)
	v_mfma_f32_16x16x32_bf16 v[152:155], v[88:91], v[68:71], v[152:155]
	s_waitcnt lgkmcnt(7)
	v_mfma_f32_16x16x32_bf16 v[104:107], v[104:107], v[8:11], v[152:155]
	s_waitcnt lgkmcnt(6)
	v_mfma_f32_16x16x32_bf16 v[104:107], v[132:135], v[12:15], v[104:107]
	s_waitcnt lgkmcnt(5)
	v_mfma_f32_16x16x32_bf16 v[104:107], v[144:147], v[16:19], v[104:107]
	s_waitcnt lgkmcnt(4)
	v_mfma_f32_16x16x32_bf16 v[104:107], v[148:151], v[20:23], v[104:107]
	s_waitcnt lgkmcnt(3)
	v_mfma_f32_16x16x32_bf16 v[104:107], v[178:181], v[24:27], v[104:107]
	s_waitcnt lgkmcnt(2)
	v_mfma_f32_16x16x32_bf16 v[104:107], v[184:187], v[28:31], v[104:107]
	s_waitcnt lgkmcnt(1)
	v_mfma_f32_16x16x32_bf16 v[104:107], v[188:191], v[32:35], v[104:107]
	s_waitcnt lgkmcnt(0)
	v_mfma_f32_16x16x32_bf16 v[104:107], v[192:195], v[36:39], v[104:107]
	s_cbranch_execnz .LBB0_139

; #define LBAR() do { asm volatile("s_waitcnt lgkmcnt(0)" ::: "memory"); __builtin_amdgcn_s_barrier(); asm volatile("" ::: "memory"); } while (0)
; #define RO_WRITE(rv, rs, buf) do { _Pragma("unroll") for (int i = 0; i < 2; ++i) { const int q = tid + 512 * i; *(LAS v4u*)(lds + (buf) + (q >> 4) * VROW + (q & 15) * 16) = rv[i]; } \
;             if (cross) { _Pragma("unroll") for (int i = 0; i < 4; ++i) { const int q = tid + 512 * i; *(LAS v4u*)(lds + (buf) + VTB + (q >> 5) * SROW + (q & 31) * 16) = rs[i]; } } } while (0)
; __device__ __forceinline__ void ret_out_phase(LAS unsigned char* lds, const bf16* PROJ, const bf16* KVT, const bf16* ST, bf16* Y, float* RN, int G, int bid) {
;     ...
; #pragma unroll 1
;         for (int ec = 0; ec < 8; ec += 2) {
;             RO_BODY(ec, BUF0);
;             RO_WRITE(rvA, rsA, BUF1); LBAR();
;             if (ec + 2 < 8) RO_LOAD(rvA, rsA, ec + 2);
;             RO_BODY(ec + 1, BUF1);
;             if (ec + 2 < 8) { RO_WRITE(rvA, rsA, BUF0); LBAR(); RO_LOAD(rvA, rsA, ec + 3); }
.LBB0_142:
	s_waitcnt vmcnt(1) lgkmcnt(2)
	s_nop 4
	v_lshlrev_b32_e32 v92, 16, v84
	v_mul_f32_e32 v93, 0xbfb8aa3b, v92
	v_exp_f32_e32 v93, v93
	v_pk_mul_f32 v[136:137], v[114:115], v[106:107]
	v_pk_mul_f32 v[138:139], v[112:113], v[104:105]
	v_and_b32_e32 v84, 0xffff0000, v84
	s_waitcnt lgkmcnt(0)
	v_cvt_pk_bf16_f32 v88, v138, v139
	v_cvt_pk_bf16_f32 v89, v136, v137
	ds_write_b64 v175, v[88:89] offset:96
	ds_read_b128 v[88:91], v176
	v_add_f32_e32 v93, 1.0, v93
	v_rcp_f32_e32 v93, v93
	s_mov_b32 s4, 0x23700000
	v_lshl_add_u64 v[144:145], v[122:123], 0, s[0:1]
	v_mul_f32_e32 v92, v93, v92
	s_waitcnt lgkmcnt(0)
	v_lshlrev_b32_e32 v93, 16, v88
	v_mul_f32_e32 v92, v92, v93
	v_mul_f32_e32 v93, 0xbfb8aa3b, v84
	v_exp_f32_e32 v93, v93
	v_and_b32_e32 v88, 0xffff0000, v88
	v_add_f32_e32 v93, 1.0, v93
	v_rcp_f32_e32 v93, v93
	s_nop 0
	v_mul_f32_e32 v84, v93, v84
	v_mul_f32_e32 v84, v84, v88
	v_lshlrev_b32_e32 v88, 16, v85
	v_cvt_pk_bf16_f32 v84, v92, v84
	v_mul_f32_e32 v92, 0xbfb8aa3b, v88
	v_exp_f32_e32 v92, v92
	v_and_b32_e32 v85, 0xffff0000, v85
	v_add_f32_e32 v92, 1.0, v92
	v_rcp_f32_e32 v92, v92
	s_nop 0
	v_mul_f32_e32 v88, v92, v88
	v_lshlrev_b32_e32 v92, 16, v89
	v_mul_f32_e32 v88, v88, v92
	v_mul_f32_e32 v92, 0xbfb8aa3b, v85
	v_exp_f32_e32 v92, v92
	v_and_b32_e32 v89, 0xffff0000, v89
	v_add_f32_e32 v92, 1.0, v92
	v_rcp_f32_e32 v92, v92
	s_nop 0
	v_mul_f32_e32 v85, v92, v85
	v_mul_f32_e32 v85, v85, v89
	v_cvt_pk_bf16_f32 v85, v88, v85
	v_lshlrev_b32_e32 v88, 16, v86
	v_mul_f32_e32 v89, 0xbfb8aa3b, v88
	v_exp_f32_e32 v89, v89
	v_and_b32_e32 v86, 0xffff0000, v86
	v_add_f32_e32 v89, 1.0, v89
	v_rcp_f32_e32 v89, v89
	s_nop 0
	v_mul_f32_e32 v88, v89, v88
	v_lshlrev_b32_e32 v89, 16, v90
	v_mul_f32_e32 v88, v88, v89
	v_mul_f32_e32 v89, 0xbfb8aa3b, v86
	v_exp_f32_e32 v89, v89
	s_nop 0
	v_add_f32_e32 v89, 1.0, v89
	v_rcp_f32_e32 v89, v89
	s_nop 0
	v_mul_f32_e32 v86, v89, v86
	v_and_b32_e32 v89, 0xffff0000, v90
	v_mul_f32_e32 v86, v86, v89
	v_cvt_pk_bf16_f32 v86, v88, v86
	v_lshlrev_b32_e32 v88, 16, v87
	v_mul_f32_e32 v89, 0xbfb8aa3b, v88
	v_exp_f32_e32 v89, v89
	v_and_b32_e32 v87, 0xffff0000, v87
	v_add_f32_e32 v89, 1.0, v89
	v_rcp_f32_e32 v89, v89
	s_nop 0
	v_mul_f32_e32 v88, v89, v88
	v_lshlrev_b32_e32 v89, 16, v91
	v_mul_f32_e32 v88, v88, v89
	v_mul_f32_e32 v89, 0xbfb8aa3b, v87
	v_exp_f32_e32 v89, v89
	s_nop 0
	v_add_f32_e32 v89, 1.0, v89
	v_rcp_f32_e32 v89, v89
	s_nop 0
	v_mul_f32_e32 v87, v89, v87
	v_and_b32_e32 v89, 0xffff0000, v91
	v_mul_f32_e32 v87, v87, v89
	v_cvt_pk_bf16_f32 v87, v88, v87
	v_lshl_add_u64 v[88:89], v[120:121], 0, s[0:1]
	v_add_co_u32_e32 v146, vcc, s4, v88
	s_waitcnt vmcnt(0)
	v_lshlrev_b32_e32 v88, 16, v80
	v_addc_co_u32_e32 v147, vcc, 0, v89, vcc
	v_mul_f32_e32 v89, 0xbfb8aa3b, v88
	v_exp_f32_e32 v89, v89
	global_store_dwordx4 v[146:147], v[84:87], off nt
	ds_read_b128 v[84:87], v176 offset:1152
	v_and_b32_e32 v80, 0xffff0000, v80
	v_add_f32_e32 v89, 1.0, v89
	v_rcp_f32_e32 v89, v89
	s_nop 0
	v_mul_f32_e32 v88, v89, v88
	s_waitcnt lgkmcnt(0)
	v_lshlrev_b32_e32 v89, 16, v84
	v_mul_f32_e32 v88, v88, v89
	v_mul_f32_e32 v89, 0xbfb8aa3b, v80
	v_exp_f32_e32 v89, v89
	v_and_b32_e32 v84, 0xffff0000, v84
	v_add_f32_e32 v89, 1.0, v89
	v_rcp_f32_e32 v89, v89
	s_nop 0
	v_mul_f32_e32 v80, v89, v80
	v_mul_f32_e32 v80, v80, v84
	v_lshlrev_b32_e32 v84, 16, v81
	v_cvt_pk_bf16_f32 v80, v88, v80
	v_mul_f32_e32 v88, 0xbfb8aa3b, v84
	v_exp_f32_e32 v88, v88
	v_and_b32_e32 v81, 0xffff0000, v81
	v_add_f32_e32 v88, 1.0, v88
	v_rcp_f32_e32 v88, v88
	s_nop 0
	v_mul_f32_e32 v84, v88, v84
	v_lshlrev_b32_e32 v88, 16, v85
	v_mul_f32_e32 v84, v84, v88
	v_mul_f32_e32 v88, 0xbfb8aa3b, v81
	v_exp_f32_e32 v88, v88
	v_and_b32_e32 v85, 0xffff0000, v85
	v_add_f32_e32 v88, 1.0, v88
	v_rcp_f32_e32 v88, v88
	s_nop 0
	v_mul_f32_e32 v81, v88, v81
	v_mul_f32_e32 v81, v81, v85
	v_cvt_pk_bf16_f32 v81, v84, v81
	v_lshlrev_b32_e32 v84, 16, v82
	v_mul_f32_e32 v85, 0xbfb8aa3b, v84
	v_exp_f32_e32 v85, v85
	v_and_b32_e32 v82, 0xffff0000, v82
	v_add_f32_e32 v85, 1.0, v85
	v_rcp_f32_e32 v85, v85
	s_nop 0
	v_mul_f32_e32 v84, v85, v84
	v_lshlrev_b32_e32 v85, 16, v86
	v_mul_f32_e32 v84, v84, v85
	v_mul_f32_e32 v85, 0xbfb8aa3b, v82
	v_exp_f32_e32 v85, v85
	s_nop 0
	v_add_f32_e32 v85, 1.0, v85
	v_rcp_f32_e32 v85, v85
	s_nop 0
	v_mul_f32_e32 v82, v85, v82
	v_and_b32_e32 v85, 0xffff0000, v86
	v_mul_f32_e32 v82, v82, v85
	v_cvt_pk_bf16_f32 v82, v84, v82
	v_lshlrev_b32_e32 v84, 16, v83
	v_mul_f32_e32 v85, 0xbfb8aa3b, v84
	v_exp_f32_e32 v85, v85
	v_and_b32_e32 v83, 0xffff0000, v83
	v_add_f32_e32 v85, 1.0, v85
	v_rcp_f32_e32 v85, v85
	s_nop 0
	v_mul_f32_e32 v84, v85, v84
	v_lshlrev_b32_e32 v85, 16, v87
	v_mul_f32_e32 v84, v84, v85
	v_mul_f32_e32 v85, 0xbfb8aa3b, v83
	v_exp_f32_e32 v85, v85
	s_nop 0
	v_add_f32_e32 v85, 1.0, v85
	v_rcp_f32_e32 v85, v85
	s_nop 0
	v_mul_f32_e32 v83, v85, v83
	v_and_b32_e32 v85, 0xffff0000, v87
	v_mul_f32_e32 v83, v83, v85
	v_cvt_pk_bf16_f32 v83, v84, v83
	v_add_co_u32_e32 v84, vcc, 0x23700000, v144
	s_nop 1
	v_addc_co_u32_e32 v85, vcc, 0, v145, vcc
	s_and_b64 vcc, exec, s[38:39]
	global_store_dwordx4 v[84:85], v[80:83], off nt
	ds_write_b128 v156, v[76:79] offset:51200
	ds_write_b128 v157, v[72:75] offset:51200
	s_cbranch_vccnz .LBB0_144
	v_add_u32_e32 v80, v160, v163
	ds_write_b128 v80, v[40:43]
	v_add_u32_e32 v80, v160, v164
	ds_write_b128 v80, v[44:47]
	v_add_u32_e32 v80, v160, v165
	ds_write_b128 v80, v[48:51]
	v_add_u32_e32 v80, v160, v166
	ds_write_b128 v80, v[52:55]
.LBB0_144:
	s_cmp_lt_u32 s22, 6
	s_waitcnt lgkmcnt(0)
	s_barrier
	s_cselect_b64 s[10:11], -1, 0
	s_cmp_gt_u32 s22, 5
	s_cselect_b64 s[4:5], -1, 0
	s_and_b64 vcc, exec, s[4:5]
	v_add_u32_e32 v178, s3, v172
	v_add_u32_e32 v177, s3, v171
	s_cbranch_vccnz .LBB0_147
	v_add_u32_e32 v72, 0x880, v178
	s_movk_i32 s23, 0x4080
	v_add_u32_e32 v74, 0x880, v177
	v_mad_i64_i32 v[72:73], s[12:13], v72, s23, v[108:109]
	v_mad_i64_i32 v[74:75], s[12:13], v74, s23, v[108:109]
	global_load_dwordx4 v[76:79], v[72:73], off nt
	s_nop 0
	global_load_dwordx4 v[72:75], v[74:75], off nt
	s_and_b64 vcc, exec, s[38:39]
	s_cbranch_vccnz .LBB0_147
	v_add_u32_e32 v40, s3, v170
	v_add_u32_e32 v42, s3, v169
	v_add_u32_e32 v48, s3, v168
	v_add_u32_e32 v50, s3, v167
	v_add_u32_e32 v40, 0x80, v40
	v_add_u32_e32 v42, 0x80, v42
	v_add_u32_e32 v48, 0x80, v48
	v_add_u32_e32 v50, 0x80, v50
	v_ashrrev_i32_e32 v41, 31, v40
	v_ashrrev_i32_e32 v43, 31, v42
	v_ashrrev_i32_e32 v49, 31, v48
	v_ashrrev_i32_e32 v51, 31, v50
	v_lshlrev_b64 v[40:41], 9, v[40:41]
	v_lshlrev_b64 v[42:43], 9, v[42:43]
	v_lshlrev_b64 v[48:49], 9, v[48:49]
	v_lshlrev_b64 v[50:51], 9, v[50:51]
	v_lshl_add_u64 v[40:41], v[116:117], 0, v[40:41]
	v_lshl_add_u64 v[44:45], v[116:117], 0, v[42:43]
	v_lshl_add_u64 v[48:49], v[116:117], 0, v[48:49]
	v_lshl_add_u64 v[52:53], v[116:117], 0, v[50:51]
	global_load_dwordx4 v[40:43], v[40:41], off nt
	s_nop 0
	global_load_dwordx4 v[44:47], v[44:45], off nt
	s_nop 0
	global_load_dwordx4 v[48:51], v[48:49], off nt
	s_nop 0
	global_load_dwordx4 v[52:55], v[52:53], off nt

.LBB0_153:
	s_waitcnt lgkmcnt(0)
	v_add_co_u32_e32 v80, vcc, 0xf519000, v140
	s_nop 5
	v_pk_mul_f32 v[152:153], v[114:115], v[98:99]
	v_addc_co_u32_e32 v81, vcc, 0, v141, vcc
	v_pk_mul_f32 v[154:155], v[112:113], v[96:97]
	s_and_b64 vcc, exec, s[38:39]
	v_cvt_pk_bf16_f32 v88, v154, v155
	v_cvt_pk_bf16_f32 v89, v152, v153
	global_load_dwordx4 v[84:87], v[142:143], off offset:128 nt
	s_nop 0
	global_load_dwordx4 v[80:83], v[80:81], off offset:128 nt
	ds_write_b64 v175, v[88:89] offset:32
	v_add_u32_e32 v88, 0xe800, v174
	ds_read2_b64 v[96:99], v88 offset0:64 offset1:68
	ds_read2_b64 v[92:95], v88 offset0:72 offset1:76
	ds_read2_b64 v[100:103], v88 offset0:80 offset1:84
	ds_read2_b64 v[88:91], v88 offset0:88 offset1:92
	s_cbranch_vccnz .LBB0_170
	ds_read_b128 v[104:107], v179 offset:8448
	ds_read_b128 v[140:143], v179 offset:8512
	ds_read_b128 v[184:187], v179 offset:8576
	ds_read_b128 v[188:191], v179 offset:8640
	s_waitcnt lgkmcnt(7)
	v_mfma_f32_16x16x32_bf16 v[192:195], v[96:99], v[56:59], 0
	ds_read_b128 v[196:199], v179 offset:8704
	ds_read_b128 v[200:203], v179 offset:8768
	ds_read_b128 v[204:207], v179 offset:8832
	ds_read_b128 v[230:233], v179 offset:8896
	s_waitcnt lgkmcnt(10)
	v_mfma_f32_16x16x32_bf16 v[192:195], v[92:95], v[60:63], v[192:195]
	s_waitcnt lgkmcnt(9)
	v_mfma_f32_16x16x32_bf16 v[192:195], v[100:103], v[64:67], v[192:195]
	s_waitcnt lgkmcnt(8)
	v_mfma_f32_16x16x32_bf16 v[192:195], v[88:91], v[68:71], v[192:195]
	s_waitcnt lgkmcnt(7)
	v_mfma_f32_16x16x32_bf16 v[104:107], v[104:107], v[8:11], v[192:195]
	s_waitcnt lgkmcnt(6)
	v_mfma_f32_16x16x32_bf16 v[104:107], v[140:143], v[12:15], v[104:107]
	s_waitcnt lgkmcnt(5)
	v_mfma_f32_16x16x32_bf16 v[104:107], v[184:187], v[16:19], v[104:107]
	s_waitcnt lgkmcnt(4)
	v_mfma_f32_16x16x32_bf16 v[104:107], v[188:191], v[20:23], v[104:107]
	s_waitcnt lgkmcnt(3)
	v_mfma_f32_16x16x32_bf16 v[104:107], v[196:199], v[24:27], v[104:107]
	s_waitcnt lgkmcnt(2)
	v_mfma_f32_16x16x32_bf16 v[104:107], v[200:203], v[28:31], v[104:107]
	s_waitcnt lgkmcnt(1)
	v_mfma_f32_16x16x32_bf16 v[104:107], v[204:207], v[32:35], v[104:107]
	s_waitcnt lgkmcnt(0)
	v_mfma_f32_16x16x32_bf16 v[104:107], v[230:233], v[36:39], v[104:107]
	s_cbranch_execnz .LBB0_156

; #define LBAR() do { asm volatile("s_waitcnt lgkmcnt(0)" ::: "memory"); __builtin_amdgcn_s_barrier(); asm volatile("" ::: "memory"); } while (0)
; #define RO_WRITE(rv, rs, buf) do { _Pragma("unroll") for (int i = 0; i < 2; ++i) { const int q = tid + 512 * i; *(LAS v4u*)(lds + (buf) + (q >> 4) * VROW + (q & 15) * 16) = rv[i]; } \
;             if (cross) { _Pragma("unroll") for (int i = 0; i < 4; ++i) { const int q = tid + 512 * i; *(LAS v4u*)(lds + (buf) + VTB + (q >> 5) * SROW + (q & 31) * 16) = rs[i]; } } } while (0)
; __device__ __forceinline__ void ret_out_phase(LAS unsigned char* lds, const bf16* PROJ, const bf16* KVT, const bf16* ST, bf16* Y, float* RN, int G, int bid) {
;     ...
; #pragma unroll 1
;         for (int ec = 0; ec < 8; ec += 2) {
;             RO_BODY(ec, BUF0);
;             RO_WRITE(rvA, rsA, BUF1); LBAR();
;             if (ec + 2 < 8) RO_LOAD(rvA, rsA, ec + 2);
;             RO_BODY(ec + 1, BUF1);
;             if (ec + 2 < 8) { RO_WRITE(rvA, rsA, BUF0); LBAR(); RO_LOAD(rvA, rsA, ec + 3); }
.LBB0_159:
	s_waitcnt vmcnt(1) lgkmcnt(3)
	s_nop 0
	v_lshlrev_b32_e32 v96, 16, v84
	v_mul_f32_e32 v97, 0xbfb8aa3b, v96
	v_exp_f32_e32 v97, v97
	s_waitcnt lgkmcnt(2)
	s_nop 1
	v_pk_mul_f32 v[92:93], v[114:115], v[106:107]
	v_pk_mul_f32 v[94:95], v[112:113], v[104:105]
	v_and_b32_e32 v84, 0xffff0000, v84
	s_waitcnt lgkmcnt(0)
	v_cvt_pk_bf16_f32 v88, v94, v95
	v_cvt_pk_bf16_f32 v89, v92, v93
	ds_write_b64 v175, v[88:89] offset:96
	ds_read_b128 v[88:91], v176
	v_add_f32_e32 v97, 1.0, v97
	v_rcp_f32_e32 v97, v97
	s_nop 0
	v_mul_f32_e32 v96, v97, v96
	s_waitcnt lgkmcnt(0)
	v_lshlrev_b32_e32 v97, 16, v88
	v_mul_f32_e32 v96, v96, v97
	v_mul_f32_e32 v97, 0xbfb8aa3b, v84
	v_exp_f32_e32 v97, v97
	v_and_b32_e32 v88, 0xffff0000, v88
	v_add_f32_e32 v97, 1.0, v97
	v_rcp_f32_e32 v97, v97
	s_nop 0
	v_mul_f32_e32 v84, v97, v84
	v_mul_f32_e32 v84, v84, v88
	v_lshlrev_b32_e32 v88, 16, v85
	v_cvt_pk_bf16_f32 v84, v96, v84
	v_mul_f32_e32 v96, 0xbfb8aa3b, v88
	v_exp_f32_e32 v96, v96
	v_and_b32_e32 v85, 0xffff0000, v85
	v_add_f32_e32 v96, 1.0, v96
	v_rcp_f32_e32 v96, v96
	s_nop 0
	v_mul_f32_e32 v88, v96, v88
	v_lshlrev_b32_e32 v96, 16, v89
	v_mul_f32_e32 v88, v88, v96
	v_mul_f32_e32 v96, 0xbfb8aa3b, v85
	v_exp_f32_e32 v96, v96
	v_and_b32_e32 v89, 0xffff0000, v89
	v_add_f32_e32 v96, 1.0, v96
	v_rcp_f32_e32 v96, v96
	s_nop 0
	v_mul_f32_e32 v85, v96, v85
	v_mul_f32_e32 v85, v85, v89
	v_cvt_pk_bf16_f32 v85, v88, v85
	v_lshlrev_b32_e32 v88, 16, v86
	v_mul_f32_e32 v89, 0xbfb8aa3b, v88
	v_exp_f32_e32 v89, v89
	v_and_b32_e32 v86, 0xffff0000, v86
	v_add_f32_e32 v89, 1.0, v89
	v_rcp_f32_e32 v89, v89
	s_nop 0
	v_mul_f32_e32 v88, v89, v88
	v_lshlrev_b32_e32 v89, 16, v90
	v_mul_f32_e32 v88, v88, v89
	v_mul_f32_e32 v89, 0xbfb8aa3b, v86
	v_exp_f32_e32 v89, v89
	s_nop 0
	v_add_f32_e32 v89, 1.0, v89
	v_rcp_f32_e32 v89, v89
	s_nop 0
	v_mul_f32_e32 v86, v89, v86
	v_and_b32_e32 v89, 0xffff0000, v90
	v_mul_f32_e32 v86, v86, v89
	v_cvt_pk_bf16_f32 v86, v88, v86
	v_lshlrev_b32_e32 v88, 16, v87
	v_mul_f32_e32 v89, 0xbfb8aa3b, v88
	v_exp_f32_e32 v89, v89
	v_and_b32_e32 v87, 0xffff0000, v87
	v_add_f32_e32 v89, 1.0, v89
	v_rcp_f32_e32 v89, v89
	s_nop 0
	v_mul_f32_e32 v88, v89, v88
	v_lshlrev_b32_e32 v89, 16, v91
	v_mul_f32_e32 v88, v88, v89
	v_mul_f32_e32 v89, 0xbfb8aa3b, v87
	v_exp_f32_e32 v89, v89
	s_nop 0
	v_add_f32_e32 v89, 1.0, v89
	v_rcp_f32_e32 v89, v89
	s_nop 0
	v_mul_f32_e32 v87, v89, v87
	v_and_b32_e32 v89, 0xffff0000, v91
	v_mul_f32_e32 v87, v87, v89
	v_cvt_pk_bf16_f32 v87, v88, v87
	s_waitcnt vmcnt(0)
	v_lshlrev_b32_e32 v88, 16, v80
	v_mul_f32_e32 v89, 0xbfb8aa3b, v88
	v_exp_f32_e32 v89, v89
	global_store_dwordx4 v[146:147], v[84:87], off offset:128 nt
	ds_read_b128 v[84:87], v176 offset:1152
	v_and_b32_e32 v80, 0xffff0000, v80
	v_add_f32_e32 v89, 1.0, v89
	v_rcp_f32_e32 v89, v89
	s_nop 0
	v_mul_f32_e32 v88, v89, v88
	s_waitcnt lgkmcnt(0)
	v_lshlrev_b32_e32 v89, 16, v84
	v_mul_f32_e32 v88, v88, v89
	v_mul_f32_e32 v89, 0xbfb8aa3b, v80
	v_exp_f32_e32 v89, v89
	v_and_b32_e32 v84, 0xffff0000, v84
	v_add_f32_e32 v89, 1.0, v89
	v_rcp_f32_e32 v89, v89
	s_nop 0
	v_mul_f32_e32 v80, v89, v80
	v_mul_f32_e32 v80, v80, v84
	v_lshlrev_b32_e32 v84, 16, v81
	v_cvt_pk_bf16_f32 v80, v88, v80
	v_mul_f32_e32 v88, 0xbfb8aa3b, v84
	v_exp_f32_e32 v88, v88
	v_and_b32_e32 v81, 0xffff0000, v81
	v_add_f32_e32 v88, 1.0, v88
	v_rcp_f32_e32 v88, v88
	s_nop 0
	v_mul_f32_e32 v84, v88, v84
	v_lshlrev_b32_e32 v88, 16, v85
	v_mul_f32_e32 v84, v84, v88
	v_mul_f32_e32 v88, 0xbfb8aa3b, v81
	v_exp_f32_e32 v88, v88
	v_and_b32_e32 v85, 0xffff0000, v85
	v_add_f32_e32 v88, 1.0, v88
	v_rcp_f32_e32 v88, v88
	s_nop 0
	v_mul_f32_e32 v81, v88, v81
	v_mul_f32_e32 v81, v81, v85
	v_cvt_pk_bf16_f32 v81, v84, v81
	v_lshlrev_b32_e32 v84, 16, v82
	v_mul_f32_e32 v85, 0xbfb8aa3b, v84
	v_exp_f32_e32 v85, v85
	v_and_b32_e32 v82, 0xffff0000, v82
	v_add_f32_e32 v85, 1.0, v85
	v_rcp_f32_e32 v85, v85
	s_nop 0
	v_mul_f32_e32 v84, v85, v84
	v_lshlrev_b32_e32 v85, 16, v86
	v_mul_f32_e32 v84, v84, v85
	v_mul_f32_e32 v85, 0xbfb8aa3b, v82
	v_exp_f32_e32 v85, v85
	s_nop 0
	v_add_f32_e32 v85, 1.0, v85
	v_rcp_f32_e32 v85, v85
	s_nop 0
	v_mul_f32_e32 v82, v85, v82
	v_and_b32_e32 v85, 0xffff0000, v86
	v_mul_f32_e32 v82, v82, v85
	v_cvt_pk_bf16_f32 v82, v84, v82
	v_lshlrev_b32_e32 v84, 16, v83
	v_mul_f32_e32 v85, 0xbfb8aa3b, v84
	v_exp_f32_e32 v85, v85
	v_and_b32_e32 v83, 0xffff0000, v83
	v_add_f32_e32 v85, 1.0, v85
	v_rcp_f32_e32 v85, v85
	s_nop 0
	v_mul_f32_e32 v84, v85, v84
	v_lshlrev_b32_e32 v85, 16, v87
	v_mul_f32_e32 v84, v84, v85
	v_mul_f32_e32 v85, 0xbfb8aa3b, v83
	v_exp_f32_e32 v85, v85
	s_nop 0
	v_add_f32_e32 v85, 1.0, v85
	v_rcp_f32_e32 v85, v85
	s_nop 0
	v_mul_f32_e32 v83, v85, v83
	v_and_b32_e32 v85, 0xffff0000, v87
	v_mul_f32_e32 v83, v83, v85
	v_cvt_pk_bf16_f32 v83, v84, v83
	v_add_co_u32_e32 v84, vcc, 0x23700000, v144
	s_nop 1
	v_addc_co_u32_e32 v85, vcc, 0, v145, vcc
	s_andn2_b64 vcc, exec, s[10:11]
	global_store_dwordx4 v[84:85], v[80:83], off offset:128 nt
	s_cbranch_vccnz .LBB0_129
	s_and_b64 vcc, exec, s[38:39]
	ds_write_b128 v156, v[76:79]
	ds_write_b128 v157, v[72:75]
	s_cbranch_vccnz .LBB0_162
	v_add_u32_e32 v72, v110, v163
	ds_write_b128 v72, v[40:43] offset:17408
	v_add_u32_e32 v72, v110, v164
	ds_write_b128 v72, v[44:47] offset:17408
	v_add_u32_e32 v72, v110, v165
	ds_write_b128 v72, v[48:51] offset:17408
	v_add_u32_e32 v72, v110, v166
	ds_write_b128 v72, v[52:55] offset:17408
.LBB0_162:
	v_add_u32_e32 v72, 0x8c0, v178
	s_movk_i32 s12, 0x4080
	v_add_u32_e32 v74, 0x8c0, v177
	s_waitcnt lgkmcnt(0)
	s_barrier
	v_mad_i64_i32 v[72:73], s[10:11], v72, s12, v[108:109]
	v_mad_i64_i32 v[74:75], s[10:11], v74, s12, v[108:109]
	global_load_dwordx4 v[76:79], v[72:73], off nt
	s_nop 0
	global_load_dwordx4 v[72:75], v[74:75], off nt
	s_and_b64 vcc, exec, s[38:39]
	s_cbranch_vccnz .LBB0_129
	v_add_u32_e32 v40, s3, v170
	v_add_u32_e32 v42, s3, v169
	v_add_u32_e32 v48, s3, v168
	v_add_u32_e32 v50, s3, v167
	v_add_u32_e32 v40, 0xc0, v40
	v_add_u32_e32 v42, 0xc0, v42
	v_add_u32_e32 v48, 0xc0, v48
	v_add_u32_e32 v50, 0xc0, v50
	v_ashrrev_i32_e32 v41, 31, v40
	v_ashrrev_i32_e32 v43, 31, v42
	v_ashrrev_i32_e32 v49, 31, v48
	v_ashrrev_i32_e32 v51, 31, v50
	v_lshlrev_b64 v[40:41], 9, v[40:41]
	v_lshlrev_b64 v[42:43], 9, v[42:43]
	v_lshlrev_b64 v[48:49], 9, v[48:49]
	v_lshlrev_b64 v[50:51], 9, v[50:51]
	v_lshl_add_u64 v[40:41], v[116:117], 0, v[40:41]
	v_lshl_add_u64 v[44:45], v[116:117], 0, v[42:43]
	v_lshl_add_u64 v[48:49], v[116:117], 0, v[48:49]
	v_lshl_add_u64 v[52:53], v[116:117], 0, v[50:51]
	global_load_dwordx4 v[40:43], v[40:41], off nt
	s_nop 0
	global_load_dwordx4 v[44:47], v[44:45], off nt
	s_nop 0
	global_load_dwordx4 v[48:51], v[48:49], off nt
	s_nop 0
	global_load_dwordx4 v[52:55], v[52:53], off nt
	s_branch .LBB0_129
